# merge chained epilogue: address calc + 8 gate loads moved above the pre-epilogue alignment barrier (on top of the gate epilogue reschedule)
# baseline (speedup 1.0000x reference)
; #define PG8_STAGE(bufoff, gbase, voff) do { _Pragma("unroll") for (int _i = 0; _i < 2; ++_i) \
;         __builtin_amdgcn_global_load_lds((const unsigned*)((const char*)(gbase) + (voff)[_i]), (PG8_LAS unsigned*)(lds + (bufoff) + ldsw + _i * 8192), 16, 0, 0); } while (0)
; #define PG8_LDA(dst, b, h) do { _Pragma("unroll") for (int m = 0; m < 4; ++m) _Pragma("unroll") for (int k = 0; k < 2; ++k) dst[m][k] = *(const PG8_LAS bf16x8*)(lds + PG8_SA(b, h) + aoff + m * 2048 + k * 1024); } while (0)
; #define PG8_LDB(dst, b, h) do { _Pragma("unroll") for (int n = 0; n < 2; ++n) _Pragma("unroll") for (int k = 0; k < 2; ++k) dst[n][k] = *(const PG8_LAS bf16x8*)(lds + PG8_SB(b, h) + boff + n * 2048 + k * 1024); } while (0)
; #define PG8_WAIT_V(n) asm volatile("s_waitcnt vmcnt(" #n ")" ::: "memory")
; #define PG8_WAIT_L(n) asm volatile("s_waitcnt lgkmcnt(" #n ")" ::: "memory")
; #define PG8_BAR __builtin_amdgcn_s_barrier()
; #define PG8_SCHED __builtin_amdgcn_sched_barrier(0)
; template <class Epi, class Sched, class Gemm, bool ALIGN_EPI = false, bool SP2 = false>
; __device__ __forceinline__ void gemm_phase(PG8_LAS unsigned char* lds, const Gemm g, const Sched& S, const Epi& E) {
;     ...
;             PG8_LDB(B0, 0, 0); PG8_LDB(B1, 0, 1); PG8_SCHED; PG8_LDA(At, 0, 0); PG8_STAGE(PG8_SA(1, 1), a1 + hstepA, voffA);
;             PG8_WAIT_V(8); PG8_WAIT_L(0); PG8_BAR; PG8_MMA(0, 0, At, B0); PG8_MMA(0, 1, At, B1); PG8_BAR; PG8_SCHED;
;             PG8_LDA(At, 0, 1); PG8_STAGE(PG8_SB(0, 0), b2, voffB); PG8_STAGE(PG8_SB(0, 1), b2 + hB1, voffB1); PG8_STAGE(PG8_SA(0, 0), a2, voffA);
;             PG8_WAIT_V(8); PG8_WAIT_L(0); PG8_BAR; PG8_MMA(1, 0, At, B0); PG8_MMA(1, 1, At, B1); PG8_BAR; PG8_SCHED;
;             PG8_LDB(B0, 1, 0); PG8_LDB(B1, 1, 1); PG8_SCHED; PG8_LDA(At, 1, 0); PG8_STAGE(PG8_SA(0, 1), a2 + hstepA, voffA);
;             PG8_WAIT_V(8); PG8_WAIT_L(0); PG8_BAR; PG8_MMA(0, 0, At, B0); PG8_MMA(0, 1, At, B1); PG8_BAR; PG8_SCHED;
;             PG8_LDA(At, 1, 1); PG8_STAGE(PG8_SB(1, 0), b3, voffB); PG8_STAGE(PG8_SB(1, 1), b3 + hB1, voffB1); PG8_STAGE(PG8_SA(1, 0), a3, voffA);
;             PG8_WAIT_V(8);
;             if constexpr (epi_pre<Epi>::value) { if (last) E.pre(pre, cur, wr, wc, lane); }
;             PG8_WAIT_L(0); PG8_BAR; PG8_MMA(1, 0, At, B0); PG8_MMA(1, 1, At, B1); PG8_BAR; PG8_SCHED;
.LBB0_1273:
	s_add_u32 s42, s30, s36
	s_addc_u32 s43, s31, s37
	s_add_u32 s40, s42, 0x100
	s_addc_u32 s41, s43, 0
	s_and_b64 s[38:39], s[2:3], exec
	s_cselect_b32 s39, s1, s41
	s_cselect_b32 s38, s23, s40
	s_add_u32 s36, s28, s36
	s_addc_u32 s37, s29, s37
	s_add_u32 s36, s36, 0x100
	s_addc_u32 s37, s37, 0
	s_and_b64 s[2:3], s[2:3], exec
	s_cselect_b32 s41, s21, s37
	s_cselect_b32 s40, s67, s36
	s_add_u32 s74, s42, 0x40080
	s_addc_u32 s75, s43, 0
	s_add_i32 s77, s61, s49
	s_add_i32 m0, s50, 0xc000
	s_add_i32 s76, s50, 0xe000
	s_add_i32 s78, s77, 0x2000
	v_add_u32_e32 v2, s61, v184
	s_add_u32 s42, s40, 0x1000
	ds_read_b128 v[158:161], v2
	ds_read_b128 v[162:165], v2 offset:1024
	ds_read_b128 v[186:189], v2 offset:2048
	ds_read_b128 v[190:193], v2 offset:3072
	v_add_u32_e32 v2, s62, v184
	s_addc_u32 s43, s41, 0
	s_add_i32 s79, s62, s49
	ds_read_b128 v[138:141], v2
	ds_read_b128 v[142:145], v2 offset:1024
	ds_read_b128 v[146:149], v2 offset:2048
	ds_read_b128 v[134:137], v2 offset:3072
	s_add_i32 s80, s79, 0x2000
	s_add_i32 s73, 0, 0x18000
	s_add_i32 s72, 0, 0x1c000
	s_add_u32 s2, s38, 0x40000
	s_addc_u32 s3, s39, 0
	s_add_i32 s69, s73, s49
	s_add_i32 s68, s69, 0x2000
	s_add_u32 s36, s40, 0x1080
	s_addc_u32 s37, s41, 0
	s_add_i32 s71, s72, s49
	s_add_i32 s70, s71, 0x2000
	v_lshl_add_u64 v[4:5], s[74:75], 0, v[166:167]
	ds_read_b128 v[150:153], v185
	ds_read_b128 v[154:157], v185 offset:1024
	ds_read_b128 v[194:197], v185 offset:2048
	ds_read_b128 v[198:201], v185 offset:3072
	ds_read_b128 v[202:205], v185 offset:4096
	ds_read_b128 v[206:209], v185 offset:5120
	ds_read_b128 v[210:213], v185 offset:6144
	ds_read_b128 v[214:217], v185 offset:7168
	global_load_lds_dwordx4 v[4:5], off
	v_lshl_add_u64 v[4:5], s[74:75], 0, v[170:171]
	s_mov_b32 m0, s76
	s_nop 0
	global_load_lds_dwordx4 v[4:5], off
	s_waitcnt vmcnt(8)
	s_waitcnt lgkmcnt(0)
	s_barrier
	s_setprio 1
	s_waitcnt lgkmcnt(0)
	v_mfma_f32_16x16x32_bf16 v[218:221], v[158:161], v[150:153], v[78:81]
	v_mfma_f32_16x16x32_bf16 v[78:81], v[162:165], v[154:157], v[218:221]
	v_mfma_f32_16x16x32_bf16 v[222:225], v[186:189], v[150:153], v[62:65]
	v_mfma_f32_16x16x32_bf16 v[226:229], v[158:161], v[194:197], v[130:133]
	v_mfma_f32_16x16x32_bf16 v[230:233], v[186:189], v[194:197], v[126:129]
	v_mfma_f32_16x16x32_bf16 v[234:237], v[158:161], v[202:205], v[74:77]
	v_mfma_f32_16x16x32_bf16 v[238:241], v[186:189], v[202:205], v[102:105]
	v_mfma_f32_16x16x32_bf16 v[218:221], v[158:161], v[210:213], v[122:125]
	v_mfma_f32_16x16x32_bf16 v[114:117], v[186:189], v[210:213], v[114:117]
	v_mfma_f32_16x16x32_bf16 v[62:65], v[190:193], v[154:157], v[222:225]
	v_mfma_f32_16x16x32_bf16 v[130:133], v[162:165], v[198:201], v[226:229]
	v_mfma_f32_16x16x32_bf16 v[126:129], v[190:193], v[198:201], v[230:233]
	v_mfma_f32_16x16x32_bf16 v[74:77], v[162:165], v[206:209], v[234:237]
	v_mfma_f32_16x16x32_bf16 v[102:105], v[190:193], v[206:209], v[238:241]
	v_mfma_f32_16x16x32_bf16 v[122:125], v[162:165], v[214:217], v[218:221]
	v_mfma_f32_16x16x32_bf16 v[114:117], v[190:193], v[214:217], v[114:117]
	s_setprio 0
	s_setprio 1
	v_mfma_f32_16x16x32_bf16 v[218:221], v[138:141], v[150:153], v[50:53]
	v_mfma_f32_16x16x32_bf16 v[50:53], v[142:145], v[154:157], v[218:221]
	v_mfma_f32_16x16x32_bf16 v[222:225], v[146:149], v[150:153], v[30:33]
	v_mfma_f32_16x16x32_bf16 v[226:229], v[138:141], v[194:197], v[110:113]
	v_mfma_f32_16x16x32_bf16 v[230:233], v[146:149], v[194:197], v[34:37]
	v_mfma_f32_16x16x32_bf16 v[234:237], v[138:141], v[202:205], v[46:49]
	v_mfma_f32_16x16x32_bf16 v[238:241], v[146:149], v[202:205], v[18:21]
	v_mfma_f32_16x16x32_bf16 v[150:153], v[138:141], v[210:213], v[90:93]
	v_mfma_f32_16x16x32_bf16 v[26:29], v[146:149], v[210:213], v[26:29]
	v_mfma_f32_16x16x32_bf16 v[30:33], v[134:137], v[154:157], v[222:225]
	v_mfma_f32_16x16x32_bf16 v[110:113], v[142:145], v[198:201], v[226:229]
	v_mfma_f32_16x16x32_bf16 v[34:37], v[134:137], v[198:201], v[230:233]
	v_mfma_f32_16x16x32_bf16 v[46:49], v[142:145], v[206:209], v[234:237]
	v_mfma_f32_16x16x32_bf16 v[18:21], v[134:137], v[206:209], v[238:241]
	v_mfma_f32_16x16x32_bf16 v[90:93], v[142:145], v[214:217], v[150:153]
	v_mfma_f32_16x16x32_bf16 v[26:29], v[134:137], v[214:217], v[26:29]
	s_setprio 0
	s_barrier
	s_mov_b32 m0, s77
	v_lshl_add_u64 v[150:151], s[40:41], 0, v[168:169]
	ds_read_b128 v[194:197], v185 offset:16384
	ds_read_b128 v[198:201], v185 offset:17408
	ds_read_b128 v[202:205], v185 offset:18432
	ds_read_b128 v[206:209], v185 offset:19456
	ds_read_b128 v[210:213], v185 offset:20480
	ds_read_b128 v[214:217], v185 offset:21504
	ds_read_b128 v[218:221], v185 offset:22528
	ds_read_b128 v[222:225], v185 offset:23552
	global_load_lds_dwordx4 v[150:151], off
	v_lshl_add_u64 v[152:153], s[40:41], 0, v[172:173]
	s_mov_b32 m0, s78
	v_lshl_add_u64 v[4:5], s[42:43], 0, v[168:169]
	global_load_lds_dwordx4 v[152:153], off
	s_mov_b32 m0, s79
	v_lshl_add_u64 v[154:155], s[38:39], 0, v[166:167]
	global_load_lds_dwordx4 v[4:5], off
	v_lshl_add_u64 v[4:5], s[42:43], 0, v[172:173]
	s_mov_b32 m0, s80
	v_lshl_add_u64 v[156:157], s[38:39], 0, v[170:171]
	global_load_lds_dwordx4 v[4:5], off
	s_mov_b32 m0, s50
	s_nop 0
	global_load_lds_dwordx4 v[154:155], off
	s_mov_b32 m0, s51
	s_nop 0
	global_load_lds_dwordx4 v[156:157], off
	s_waitcnt vmcnt(8)
	s_waitcnt lgkmcnt(0)
	s_barrier
; #define PG8_STAGE(bufoff, gbase, voff) do { _Pragma("unroll") for (int _i = 0; _i < 2; ++_i) \
;         __builtin_amdgcn_global_load_lds((const unsigned*)((const char*)(gbase) + (voff)[_i]), (PG8_LAS unsigned*)(lds + (bufoff) + ldsw + _i * 8192), 16, 0, 0); } while (0)
; #define PG8_LDA(dst, b, h) do { _Pragma("unroll") for (int m = 0; m < 4; ++m) _Pragma("unroll") for (int k = 0; k < 2; ++k) dst[m][k] = *(const PG8_LAS bf16x8*)(lds + PG8_SA(b, h) + aoff + m * 2048 + k * 1024); } while (0)
; #define PG8_LDB(dst, b, h) do { _Pragma("unroll") for (int n = 0; n < 2; ++n) _Pragma("unroll") for (int k = 0; k < 2; ++k) dst[n][k] = *(const PG8_LAS bf16x8*)(lds + PG8_SB(b, h) + boff + n * 2048 + k * 1024); } while (0)
; #define PG8_WAIT_V(n) asm volatile("s_waitcnt vmcnt(" #n ")" ::: "memory")
; #define PG8_WAIT_L(n) asm volatile("s_waitcnt lgkmcnt(" #n ")" ::: "memory")
; #define PG8_BAR __builtin_amdgcn_s_barrier()
; #define PG8_SCHED __builtin_amdgcn_sched_barrier(0)
; template <class Epi, class Sched, class Gemm, bool ALIGN_EPI = false, bool SP2 = false>
; __device__ __forceinline__ void gemm_phase(PG8_LAS unsigned char* lds, const Gemm g, const Sched& S, const Epi& E) {
;     ...
;             PG8_LDB(B0, 0, 0); PG8_LDB(B1, 0, 1); PG8_SCHED; PG8_LDA(At, 0, 0); PG8_STAGE(PG8_SA(1, 1), a1 + hstepA, voffA);
;             PG8_WAIT_V(8); PG8_WAIT_L(0); PG8_BAR; PG8_MMA(0, 0, At, B0); PG8_MMA(0, 1, At, B1); PG8_BAR; PG8_SCHED;
;             PG8_LDA(At, 0, 1); PG8_STAGE(PG8_SB(0, 0), b2, voffB); PG8_STAGE(PG8_SB(0, 1), b2 + hB1, voffB1); PG8_STAGE(PG8_SA(0, 0), a2, voffA);
;             PG8_WAIT_V(8); PG8_WAIT_L(0); PG8_BAR; PG8_MMA(1, 0, At, B0); PG8_MMA(1, 1, At, B1); PG8_BAR; PG8_SCHED;
;             PG8_LDB(B0, 1, 0); PG8_LDB(B1, 1, 1); PG8_SCHED; PG8_LDA(At, 1, 0); PG8_STAGE(PG8_SA(0, 1), a2 + hstepA, voffA);
;             PG8_WAIT_V(8); PG8_WAIT_L(0); PG8_BAR; PG8_MMA(0, 0, At, B0); PG8_MMA(0, 1, At, B1); PG8_BAR; PG8_SCHED;
;             PG8_LDA(At, 1, 1); PG8_STAGE(PG8_SB(1, 0), b3, voffB); PG8_STAGE(PG8_SB(1, 1), b3 + hB1, voffB1); PG8_STAGE(PG8_SA(1, 0), a3, voffA);
;             PG8_WAIT_V(8);
;             if constexpr (epi_pre<Epi>::value) { if (last) E.pre(pre, cur, wr, wc, lane); }
;             PG8_WAIT_L(0); PG8_BAR; PG8_MMA(1, 0, At, B0); PG8_MMA(1, 1, At, B1); PG8_BAR; PG8_SCHED;
	s_setprio 1
	s_waitcnt lgkmcnt(0)
	v_mfma_f32_16x16x32_bf16 v[226:229], v[158:161], v[194:197], v[70:73]
	v_mfma_f32_16x16x32_bf16 v[70:73], v[162:165], v[198:201], v[226:229]
	v_mfma_f32_16x16x32_bf16 v[230:233], v[186:189], v[194:197], v[58:61]
	v_mfma_f32_16x16x32_bf16 v[234:237], v[158:161], v[202:205], v[98:101]
	v_mfma_f32_16x16x32_bf16 v[238:241], v[186:189], v[202:205], v[86:89]
	v_mfma_f32_16x16x32_bf16 v[242:245], v[158:161], v[210:213], v[66:69]
	v_mfma_f32_16x16x32_bf16 v[246:249], v[186:189], v[210:213], v[94:97]
	v_mfma_f32_16x16x32_bf16 v[226:229], v[158:161], v[218:221], v[118:121]
	v_mfma_f32_16x16x32_bf16 v[106:109], v[186:189], v[218:221], v[106:109]
	v_mfma_f32_16x16x32_bf16 v[58:61], v[190:193], v[198:201], v[230:233]
	v_mfma_f32_16x16x32_bf16 v[98:101], v[162:165], v[206:209], v[234:237]
	v_mfma_f32_16x16x32_bf16 v[86:89], v[190:193], v[206:209], v[238:241]
	v_mfma_f32_16x16x32_bf16 v[66:69], v[162:165], v[214:217], v[242:245]
	v_mfma_f32_16x16x32_bf16 v[94:97], v[190:193], v[214:217], v[246:249]
	v_mfma_f32_16x16x32_bf16 v[118:121], v[162:165], v[222:225], v[226:229]
	v_mfma_f32_16x16x32_bf16 v[106:109], v[190:193], v[222:225], v[106:109]
	s_setprio 0
	s_setprio 1
	v_mfma_f32_16x16x32_bf16 v[158:161], v[138:141], v[194:197], v[42:45]
	v_mfma_f32_16x16x32_bf16 v[42:45], v[142:145], v[198:201], v[158:161]
	v_mfma_f32_16x16x32_bf16 v[162:165], v[146:149], v[194:197], v[6:9]
	v_mfma_f32_16x16x32_bf16 v[186:189], v[138:141], v[202:205], v[54:57]
	v_mfma_f32_16x16x32_bf16 v[190:193], v[146:149], v[202:205], v[10:13]
	v_mfma_f32_16x16x32_bf16 v[226:229], v[138:141], v[210:213], v[38:41]
	v_mfma_f32_16x16x32_bf16 v[230:233], v[146:149], v[210:213], v[14:17]
	v_mfma_f32_16x16x32_bf16 v[158:161], v[138:141], v[218:221], v[82:85]
	v_mfma_f32_16x16x32_bf16 v[22:25], v[146:149], v[218:221], v[22:25]
	v_mfma_f32_16x16x32_bf16 v[4:7], v[134:137], v[198:201], v[162:165]
	v_mfma_f32_16x16x32_bf16 v[54:57], v[142:145], v[206:209], v[186:189]
	v_mfma_f32_16x16x32_bf16 v[10:13], v[134:137], v[206:209], v[190:193]
	v_mfma_f32_16x16x32_bf16 v[38:41], v[142:145], v[214:217], v[226:229]
	v_mfma_f32_16x16x32_bf16 v[14:17], v[134:137], v[214:217], v[230:233]
	v_mfma_f32_16x16x32_bf16 v[82:85], v[142:145], v[222:225], v[158:161]
	v_mfma_f32_16x16x32_bf16 v[22:25], v[134:137], v[222:225], v[22:25]
	s_setprio 0
	s_barrier
	v_add_u32_e32 v2, s73, v184
	ds_read_b128 v[158:161], v2
	ds_read_b128 v[162:165], v2 offset:1024
	ds_read_b128 v[186:189], v2 offset:2048
	ds_read_b128 v[190:193], v2 offset:3072
	v_add_u32_e32 v2, s72, v184
	ds_read_b128 v[138:141], v2
	ds_read_b128 v[142:145], v2 offset:1024
	ds_read_b128 v[146:149], v2 offset:2048
	ds_read_b128 v[134:137], v2 offset:3072
	s_mov_b32 m0, s52
	v_lshl_add_u64 v[8:9], s[2:3], 0, v[166:167]
	ds_read_b128 v[194:197], v185 offset:32768
	ds_read_b128 v[198:201], v185 offset:33792
	ds_read_b128 v[202:205], v185 offset:34816
	ds_read_b128 v[206:209], v185 offset:35840
	ds_read_b128 v[210:213], v185 offset:36864
	ds_read_b128 v[214:217], v185 offset:37888
	ds_read_b128 v[218:221], v185 offset:38912
	ds_read_b128 v[222:225], v185 offset:39936
	global_load_lds_dwordx4 v[8:9], off
	v_lshl_add_u64 v[8:9], s[2:3], 0, v[170:171]
	s_mov_b32 m0, s53
	s_nop 0
	global_load_lds_dwordx4 v[8:9], off
	s_waitcnt vmcnt(8)
	s_waitcnt lgkmcnt(0)
	s_barrier
	s_setprio 1
	s_waitcnt lgkmcnt(0)
	v_mfma_f32_16x16x32_bf16 v[226:229], v[158:161], v[194:197], v[78:81]
	v_mfma_f32_16x16x32_bf16 v[78:81], v[162:165], v[198:201], v[226:229]
	v_mfma_f32_16x16x32_bf16 v[230:233], v[186:189], v[194:197], v[62:65]
	v_mfma_f32_16x16x32_bf16 v[234:237], v[158:161], v[202:205], v[130:133]
	v_mfma_f32_16x16x32_bf16 v[238:241], v[186:189], v[202:205], v[126:129]
	v_mfma_f32_16x16x32_bf16 v[242:245], v[158:161], v[210:213], v[74:77]
	v_mfma_f32_16x16x32_bf16 v[246:249], v[186:189], v[210:213], v[102:105]
	v_mfma_f32_16x16x32_bf16 v[226:229], v[158:161], v[218:221], v[122:125]
	v_mfma_f32_16x16x32_bf16 v[114:117], v[186:189], v[218:221], v[114:117]
	v_mfma_f32_16x16x32_bf16 v[62:65], v[190:193], v[198:201], v[230:233]
	v_mfma_f32_16x16x32_bf16 v[130:133], v[162:165], v[206:209], v[234:237]
	v_mfma_f32_16x16x32_bf16 v[126:129], v[190:193], v[206:209], v[238:241]
	v_mfma_f32_16x16x32_bf16 v[74:77], v[162:165], v[214:217], v[242:245]
	v_mfma_f32_16x16x32_bf16 v[102:105], v[190:193], v[214:217], v[246:249]
	v_mfma_f32_16x16x32_bf16 v[122:125], v[162:165], v[222:225], v[226:229]
	v_mfma_f32_16x16x32_bf16 v[114:117], v[190:193], v[222:225], v[114:117]
	s_setprio 0
	s_setprio 1
	v_mfma_f32_16x16x32_bf16 v[226:229], v[138:141], v[194:197], v[50:53]
	v_mfma_f32_16x16x32_bf16 v[50:53], v[142:145], v[198:201], v[226:229]
	v_mfma_f32_16x16x32_bf16 v[230:233], v[146:149], v[194:197], v[30:33]
	v_mfma_f32_16x16x32_bf16 v[234:237], v[138:141], v[202:205], v[110:113]
	v_mfma_f32_16x16x32_bf16 v[238:241], v[146:149], v[202:205], v[34:37]
	v_mfma_f32_16x16x32_bf16 v[242:245], v[138:141], v[210:213], v[46:49]
	v_mfma_f32_16x16x32_bf16 v[246:249], v[146:149], v[210:213], v[18:21]
	v_mfma_f32_16x16x32_bf16 v[194:197], v[138:141], v[218:221], v[90:93]
	v_mfma_f32_16x16x32_bf16 v[26:29], v[146:149], v[218:221], v[26:29]
	v_mfma_f32_16x16x32_bf16 v[30:33], v[134:137], v[198:201], v[230:233]
	v_mfma_f32_16x16x32_bf16 v[110:113], v[142:145], v[206:209], v[234:237]
	v_mfma_f32_16x16x32_bf16 v[34:37], v[134:137], v[206:209], v[238:241]
	v_mfma_f32_16x16x32_bf16 v[46:49], v[142:145], v[214:217], v[242:245]
	v_mfma_f32_16x16x32_bf16 v[18:21], v[134:137], v[214:217], v[246:249]
	v_mfma_f32_16x16x32_bf16 v[90:93], v[142:145], v[222:225], v[194:197]
	v_mfma_f32_16x16x32_bf16 v[26:29], v[134:137], v[222:225], v[26:29]
	s_setprio 0
	s_barrier
; #define PG8_WAIT_V(n) asm volatile("s_waitcnt vmcnt(" #n ")" ::: "memory")
;     __device__ __forceinline__ void chain(f32x4 (&acc)[2][2][4][2], const Unit& u, int wr, int wc, int fr, int fq) const {
;     ...
;         const bool last = (u.sub == 3);
; template <class Epi, class Sched, class Gemm, bool ALIGN_EPI = false, bool SP2 = false>
; __device__ __forceinline__ void gemm_phase(PG8_LAS unsigned char* lds, const Gemm g, const Sched& S, const Epi& E) {
;     ...
;             PG8_WAIT_V(8); PG8_WAIT_L(0); PG8_BAR; PG8_MMA(0, 0, At, B0); PG8_MMA(0, 1, At, B1); PG8_BAR; PG8_SCHED;
;             PG8_LDA(At, 1, 1); PG8_STAGE(PG8_SB(1, 0), b3, voffB); PG8_STAGE(PG8_SB(1, 1), b3 + hB1, voffB1); PG8_STAGE(PG8_SA(1, 0), a3, voffA);
;             PG8_WAIT_V(8);
;             if constexpr (epi_pre<Epi>::value) { if (last) E.pre(pre, cur, wr, wc, lane); }
;             PG8_WAIT_L(0); PG8_BAR; PG8_MMA(1, 0, At, B0); PG8_MMA(1, 1, At, B1); PG8_BAR; PG8_SCHED;
;             } else {
;             PG8_LDB(B0, 0, 0); PG8_SCHED; PG8_LDA(At, 0, 0); PG8_STAGE(PG8_SA(1, 1), a1 + hstepA, voffA);
;             PG8_WAIT_L(8); PG8_BAR; PG8_WAIT_L(0); PG8_MMA(0, 0, At, B0); PG8_BAR; PG8_SCHED;
;             PG8_LDB(B1, 0, 1); PG8_STAGE(PG8_SB(0, 0), b2, voffB);
;             PG8_BAR; PG8_WAIT_L(0); PG8_MMA(0, 1, At, B1); PG8_BAR;
;             PG8_LDA(At, 0, 1); PG8_STAGE(PG8_SA(0, 0), a2, voffA);
;             PG8_BAR; PG8_WAIT_L(0); PG8_MMA(1, 0, At, B0); PG8_BAR; PG8_SCHED;
;             PG8_STAGE(PG8_SB(0, 1), b2 + hB1, voffB1);
;             PG8_WAIT_V(6); PG8_BAR; PG8_MMA(1, 1, At, B1); PG8_BAR;
;             PG8_LDB(B0, 1, 0); PG8_SCHED; PG8_LDA(At, 1, 0); PG8_STAGE(PG8_SA(0, 1), a2 + hstepA, voffA);
;             PG8_WAIT_L(8); PG8_BAR; PG8_WAIT_L(0); PG8_MMA(0, 0, At, B0); PG8_BAR; PG8_SCHED;
;             PG8_LDB(B1, 1, 1); PG8_STAGE(PG8_SB(1, 0), b3, voffB);
;             PG8_BAR; PG8_WAIT_L(0); PG8_MMA(0, 1, At, B1); PG8_BAR;
;             PG8_LDA(At, 1, 1); PG8_STAGE(PG8_SA(1, 0), a3, voffA);
;             PG8_BAR; PG8_WAIT_L(0); PG8_MMA(1, 0, At, B0); PG8_BAR; PG8_SCHED;
;             PG8_STAGE(PG8_SB(1, 1), b3 + hB1, voffB1);
;             PG8_WAIT_V(6); PG8_BAR; PG8_MMA(1, 1, At, B1); PG8_BAR;
;             }
;         }
;         if constexpr (ALIGN_EPI) { if (wr == 0) PG8_BAR; }
;         if constexpr (epi_chain<Epi>::value) { E.chain(acc, cur, wr, wc, fr, fq); S.done(cur); }
	s_mov_b32 m0, s69
	v_lshl_add_u64 v[8:9], v[150:151], 0, s[16:17]
	ds_read_b128 v[194:197], v185 offset:49152
	ds_read_b128 v[198:201], v185 offset:50176
	ds_read_b128 v[202:205], v185 offset:51200
	ds_read_b128 v[206:209], v185 offset:52224
	ds_read_b128 v[210:213], v185 offset:53248
	ds_read_b128 v[214:217], v185 offset:54272
	ds_read_b128 v[218:221], v185 offset:55296
	ds_read_b128 v[222:225], v185 offset:56320
	global_load_lds_dwordx4 v[8:9], off
	v_lshl_add_u64 v[8:9], v[152:153], 0, s[16:17]
	s_mov_b32 m0, s68
	s_nop 0
	global_load_lds_dwordx4 v[8:9], off
	v_lshl_add_u64 v[8:9], s[36:37], 0, v[168:169]
	s_mov_b32 m0, s71
	s_nop 0
	global_load_lds_dwordx4 v[8:9], off
	v_lshl_add_u64 v[8:9], s[36:37], 0, v[172:173]
	s_mov_b32 m0, s70
	s_nop 0
	global_load_lds_dwordx4 v[8:9], off
	v_lshl_add_u64 v[8:9], v[154:155], 0, s[16:17]
	s_mov_b32 m0, s57
	s_nop 0
	global_load_lds_dwordx4 v[8:9], off
	v_lshl_add_u64 v[8:9], v[156:157], 0, s[16:17]
	s_mov_b32 m0, s58
	s_nop 0
	global_load_lds_dwordx4 v[8:9], off
	s_waitcnt vmcnt(8)
	s_waitcnt lgkmcnt(0)
	s_barrier
	s_setprio 1
	s_waitcnt lgkmcnt(0)
	v_mfma_f32_16x16x32_bf16 v[150:153], v[158:161], v[194:197], v[70:73]
	v_mfma_f32_16x16x32_bf16 v[70:73], v[162:165], v[198:201], v[150:153]
	v_mfma_f32_16x16x32_bf16 v[154:157], v[186:189], v[194:197], v[58:61]
	v_mfma_f32_16x16x32_bf16 v[226:229], v[158:161], v[202:205], v[98:101]
	v_mfma_f32_16x16x32_bf16 v[230:233], v[186:189], v[202:205], v[86:89]
	v_mfma_f32_16x16x32_bf16 v[234:237], v[158:161], v[210:213], v[66:69]
	v_mfma_f32_16x16x32_bf16 v[238:241], v[186:189], v[210:213], v[94:97]
	v_mfma_f32_16x16x32_bf16 v[150:153], v[158:161], v[218:221], v[118:121]
	v_mfma_f32_16x16x32_bf16 v[106:109], v[186:189], v[218:221], v[106:109]
	v_mfma_f32_16x16x32_bf16 v[58:61], v[190:193], v[198:201], v[154:157]
	v_mfma_f32_16x16x32_bf16 v[98:101], v[162:165], v[206:209], v[226:229]
	v_mfma_f32_16x16x32_bf16 v[86:89], v[190:193], v[206:209], v[230:233]
	v_mfma_f32_16x16x32_bf16 v[66:69], v[162:165], v[214:217], v[234:237]
	v_mfma_f32_16x16x32_bf16 v[94:97], v[190:193], v[214:217], v[238:241]
	v_mfma_f32_16x16x32_bf16 v[118:121], v[162:165], v[222:225], v[150:153]
	v_mfma_f32_16x16x32_bf16 v[106:109], v[190:193], v[222:225], v[106:109]
	s_setprio 0
	s_setprio 1
	v_mfma_f32_16x16x32_bf16 v[150:153], v[138:141], v[194:197], v[42:45]
	v_mfma_f32_16x16x32_bf16 v[42:45], v[142:145], v[198:201], v[150:153]
	v_mfma_f32_16x16x32_bf16 v[154:157], v[146:149], v[194:197], v[4:7]
	v_mfma_f32_16x16x32_bf16 v[158:161], v[138:141], v[202:205], v[54:57]
	v_mfma_f32_16x16x32_bf16 v[162:165], v[146:149], v[202:205], v[10:13]
	v_mfma_f32_16x16x32_bf16 v[186:189], v[138:141], v[210:213], v[38:41]
	v_mfma_f32_16x16x32_bf16 v[190:193], v[146:149], v[210:213], v[14:17]
	v_mfma_f32_16x16x32_bf16 v[150:153], v[138:141], v[218:221], v[82:85]
	v_mfma_f32_16x16x32_bf16 v[22:25], v[146:149], v[218:221], v[22:25]
	v_mfma_f32_16x16x32_bf16 v[6:9], v[134:137], v[198:201], v[154:157]
	v_mfma_f32_16x16x32_bf16 v[54:57], v[142:145], v[206:209], v[158:161]
	v_mfma_f32_16x16x32_bf16 v[10:13], v[134:137], v[206:209], v[162:165]
	v_mfma_f32_16x16x32_bf16 v[38:41], v[142:145], v[214:217], v[186:189]
	v_mfma_f32_16x16x32_bf16 v[14:17], v[134:137], v[214:217], v[190:193]
	v_mfma_f32_16x16x32_bf16 v[82:85], v[142:145], v[222:225], v[150:153]
	v_mfma_f32_16x16x32_bf16 v[22:25], v[134:137], v[222:225], v[22:25]
	s_setprio 0
	s_barrier
	s_andn2_b64 vcc, exec, s[34:35]
	s_mov_b64 s[2:3], -1
	s_mov_b64 s[34:35], 0
	s_mov_b64 s[36:37], 0x100
	s_cbranch_vccz .LBB0_1273
	s_lshl_b32 s0, s0, 8
	s_lshl_b32 s1, s6, 8
	s_or_b32 s21, s0, s59
	s_lshl_b32 s0, s7, 10
	s_add_i32 s6, s1, s56
	s_add_i32 s23, s0, 0xc00
	s_cmp_eq_u32 s7, 3
	v_mov_b32_e32 v2, v1
	v_mov_b32_e32 v4, v181
	s_cselect_b64 s[0:1], -1, 0
	s_and_b64 s[2:3], s[0:1], exec
	s_cselect_b32 s2, 0, s23
	v_add_u32_e32 v2, s6, v2
	v_mul_lo_u32 v5, v2, s63
	v_lshlrev_b32_e32 v4, 4, v4
	s_cselect_b32 s28, s54, s14
	s_cselect_b32 s29, s55, s15
	s_add_i32 s3, s2, 0x400
	v_add3_u32 v180, s21, v4, v5
	s_cmp_lt_u32 s7, 2
	v_add_u32_e32 v4, s2, v180
	s_cselect_b32 s3, s3, 0
	global_load_dwordx4 v[142:145], v4, s[14:15]
	v_add_u32_e32 v4, s3, v180
	v_cndmask_b32_e64 v4, v4, 0, s[0:1]
	global_load_dwordx4 v[146:149], v4, s[28:29]
	v_add_u32_e32 v4, 0x22000, v180
	v_add_u32_e32 v138, 0x66000, v180
	v_add_u32_e32 v5, 0x44000, v180
	v_add_u32_e32 v134, s2, v4
	v_add_u32_e32 v136, s2, v138
	v_add_u32_e32 v4, s3, v4
	v_add_u32_e32 v138, s3, v138
	v_add_u32_e32 v135, s2, v5
	v_add_u32_e32 v5, s3, v5
	v_cndmask_b32_e64 v4, v4, 0, s[0:1]
	v_cndmask_b32_e64 v138, v138, 0, s[0:1]
	global_load_dwordx4 v[150:153], v134, s[14:15]
	global_load_dwordx4 v[154:157], v135, s[14:15]
	s_nop 0
	global_load_dwordx4 v[134:137], v136, s[14:15]
	v_cndmask_b32_e64 v5, v5, 0, s[0:1]
	global_load_dwordx4 v[158:161], v4, s[28:29]
	global_load_dwordx4 v[162:165], v5, s[28:29]
	s_nop 0
	global_load_dwordx4 v[138:141], v138, s[28:29]
	v_mad_u64_u32 v[4:5], s[30:31], v2, s64, v[180:181]
	s_and_b64 vcc, exec, s[18:19]
	s_cbranch_vccz .LBB0_1276
	s_barrier
; __device__ __forceinline__ unsigned cvt_pk_bf16(float lo, float hi) { return ::pk2(lo, hi); }
;     __device__ __forceinline__ void chain(f32x4 (&acc)[2][2][4][2], const Unit& u, int wr, int wc, int fr, int fq) const {
;     ...
;         for (int i = 0; i < 8; ++i) {
;             const int ai = i >> 2, m = i & 3;
;             const u32x4 g = gq[i], r = gr[i];
;             f32x4 s0, s1, s2, s3;
;             EPC_S4(s0, g.x, r.x); EPC_S4(s1, g.y, r.y); EPC_S4(s2, g.z, r.z); EPC_S4(s3, g.w, r.w);
;             const f32x4 v0 = acc[ai][0][m][0] * s0, v1 = acc[ai][0][m][1] * s1, v2 = acc[ai][1][m][0] * s2, v3 = acc[ai][1][m][1] * s3;
;             if (last) {
;                 u32x4 w0, w1; w0.x = cvt_pk_bf16(v0[0], v0[1]); w0.y = cvt_pk_bf16(v0[2], v0[3]); w0.z = cvt_pk_bf16(v1[0], v1[1]); w0.w = cvt_pk_bf16(v1[2], v1[3]);
;                 w1.x = cvt_pk_bf16(v2[0], v2[1]); w1.y = cvt_pk_bf16(v2[2], v2[3]); w1.z = cvt_pk_bf16(v3[0], v3[1]); w1.w = cvt_pk_bf16(v3[2], v3[3]);
;                 *(u32x4*)(O + (obase + EPC_OOFF(i))) = w0; *(u32x4*)(O + (obase + EPC_OOFF(i)) + 8) = w1;
;             }
.LBB0_1276:
	s_cmp_lg_u32 s7, 3
	s_waitcnt vmcnt(0)
	v_cvt_f32_ubyte3_e32 v179, v142
	v_cvt_f32_ubyte2_e32 v178, v142
	v_cvt_f32_ubyte1_e32 v183, v142
	v_cvt_f32_ubyte0_e32 v182, v142
	v_cvt_f32_ubyte3_e32 v187, v143
	v_cvt_f32_ubyte2_e32 v186, v143
	v_cvt_f32_ubyte1_e32 v189, v143
	v_cvt_f32_ubyte0_e32 v188, v143
	v_cvt_f32_ubyte3_e32 v143, v144
	v_cvt_f32_ubyte2_e32 v142, v144
	v_cvt_f32_ubyte1_e32 v191, v144
	v_cvt_f32_ubyte0_e32 v190, v144
	v_cvt_f32_ubyte0_e32 v2, v146
	v_cvt_f32_ubyte1_e32 v5, v146
	v_cvt_f32_ubyte2_e32 v144, v146
	v_cvt_f32_ubyte3_e32 v193, v146
	v_cvt_f32_ubyte0_e32 v194, v147
	v_cvt_f32_ubyte1_e32 v195, v147
	v_cvt_f32_ubyte0_e32 v198, v148
	v_cvt_f32_ubyte1_e32 v199, v148
	v_cvt_f32_ubyte2_e32 v196, v147
	v_cvt_f32_ubyte3_e32 v197, v147
	v_cvt_f32_ubyte2_e32 v200, v148
	v_cvt_f32_ubyte3_e32 v148, v148
	v_cvt_f32_ubyte0_e32 v202, v149
	v_cvt_f32_ubyte1_e32 v203, v149
	v_cvt_f32_ubyte2_e32 v204, v149
	v_rcp_iflag_f32_e32 v146, v2
	v_rcp_iflag_f32_e32 v147, v5
	v_rcp_iflag_f32_e32 v192, v144
	v_rcp_iflag_f32_e32 v193, v193
	v_rcp_iflag_f32_e32 v194, v194
	v_rcp_iflag_f32_e32 v195, v195
	v_rcp_iflag_f32_e32 v198, v198
	v_rcp_iflag_f32_e32 v199, v199
	v_cvt_f32_ubyte3_e32 v2, v149
	v_rcp_iflag_f32_e32 v196, v196
	v_rcp_iflag_f32_e32 v197, v197
	v_rcp_iflag_f32_e32 v200, v200
	v_rcp_iflag_f32_e32 v201, v148
	v_rcp_iflag_f32_e32 v202, v202
	v_rcp_iflag_f32_e32 v203, v203
	v_rcp_iflag_f32_e32 v148, v204
	v_rcp_iflag_f32_e32 v149, v2
	v_pk_mul_f32 v[146:147], v[146:147], v[182:183]
	v_pk_mul_f32 v[178:179], v[192:193], v[178:179]
	v_pk_mul_f32 v[182:183], v[194:195], v[188:189]
	v_pk_mul_f32 v[188:189], v[198:199], v[190:191]
	v_cvt_f32_ubyte3_e32 v191, v145
	v_cvt_f32_ubyte2_e32 v190, v145
	v_cvt_f32_ubyte1_e32 v193, v145
	v_cvt_f32_ubyte0_e32 v192, v145
	v_pk_mul_f32 v[186:187], v[196:197], v[186:187]
	v_pk_mul_f32 v[142:143], v[200:201], v[142:143]
	v_pk_mul_f32 v[144:145], v[202:203], v[192:193]
	v_pk_mul_f32 v[148:149], v[148:149], v[190:191]
	v_pk_mul_f32 v[80:81], v[80:81], v[178:179]
	v_pk_mul_f32 v[78:79], v[78:79], v[146:147]
	v_pk_mul_f32 v[64:65], v[64:65], v[186:187]
	v_pk_mul_f32 v[62:63], v[62:63], v[182:183]
	v_pk_mul_f32 v[52:53], v[52:53], v[142:143]
	v_pk_mul_f32 v[50:51], v[50:51], v[188:189]
	v_pk_mul_f32 v[32:33], v[32:33], v[148:149]
	v_pk_mul_f32 v[30:31], v[30:31], v[144:145]
	s_cbranch_scc1 .LBB0_1278
	v_mov_b32_e32 v5, v3
	v_cvt_pk_bf16_f32 v142, v78, v79
	v_cvt_pk_bf16_f32 v143, v80, v81
	v_cvt_pk_bf16_f32 v144, v62, v63
	v_cvt_pk_bf16_f32 v145, v64, v65
	v_lshl_add_u64 v[178:179], v[4:5], 1, s[12:13]
	v_cvt_pk_bf16_f32 v146, v50, v51
	v_cvt_pk_bf16_f32 v147, v52, v53
	v_cvt_pk_bf16_f32 v148, v30, v31
	v_cvt_pk_bf16_f32 v149, v32, v33
	global_store_dwordx4 v[178:179], v[142:145], off
	global_store_dwordx4 v[178:179], v[146:149], off offset:16

; #define PG8_STAGE(bufoff, gbase, voff) do { _Pragma("unroll") for (int _i = 0; _i < 2; ++_i) \
;         __builtin_amdgcn_global_load_lds((const unsigned*)((const char*)(gbase) + (voff)[_i]), (PG8_LAS unsigned*)(lds + (bufoff) + ldsw + _i * 8192), 16, 0, 0); } while (0)
; #define PG8_LDA(dst, b, h) do { _Pragma("unroll") for (int m = 0; m < 4; ++m) _Pragma("unroll") for (int k = 0; k < 2; ++k) dst[m][k] = *(const PG8_LAS bf16x8*)(lds + PG8_SA(b, h) + aoff + m * 2048 + k * 1024); } while (0)
; #define PG8_LDB(dst, b, h) do { _Pragma("unroll") for (int n = 0; n < 2; ++n) _Pragma("unroll") for (int k = 0; k < 2; ++k) dst[n][k] = *(const PG8_LAS bf16x8*)(lds + PG8_SB(b, h) + boff + n * 2048 + k * 1024); } while (0)
; #define PG8_WAIT_V(n) asm volatile("s_waitcnt vmcnt(" #n ")" ::: "memory")
; #define PG8_WAIT_L(n) asm volatile("s_waitcnt lgkmcnt(" #n ")" ::: "memory")
; #define PG8_BAR __builtin_amdgcn_s_barrier()
; #define PG8_SCHED __builtin_amdgcn_sched_barrier(0)
; template <class Epi, class Sched, class Gemm, bool ALIGN_EPI = false, bool SP2 = false>
; __device__ __forceinline__ void gemm_phase(PG8_LAS unsigned char* lds, const Gemm g, const Sched& S, const Epi& E) {
;     ...
;             PG8_LDB(B0, 0, 0); PG8_LDB(B1, 0, 1); PG8_SCHED; PG8_LDA(At, 0, 0); PG8_STAGE(PG8_SA(1, 1), a1 + hstepA, voffA);
;             PG8_WAIT_V(8); PG8_WAIT_L(0); PG8_BAR; PG8_MMA(0, 0, At, B0); PG8_MMA(0, 1, At, B1); PG8_BAR; PG8_SCHED;
;             PG8_LDA(At, 0, 1); PG8_STAGE(PG8_SB(0, 0), b2, voffB); PG8_STAGE(PG8_SB(0, 1), b2 + hB1, voffB1); PG8_STAGE(PG8_SA(0, 0), a2, voffA);
;             PG8_WAIT_V(8); PG8_WAIT_L(0); PG8_BAR; PG8_MMA(1, 0, At, B0); PG8_MMA(1, 1, At, B1); PG8_BAR; PG8_SCHED;
;             PG8_LDB(B0, 1, 0); PG8_LDB(B1, 1, 1); PG8_SCHED; PG8_LDA(At, 1, 0); PG8_STAGE(PG8_SA(0, 1), a2 + hstepA, voffA);
;             PG8_WAIT_V(8); PG8_WAIT_L(0); PG8_BAR; PG8_MMA(0, 0, At, B0); PG8_MMA(0, 1, At, B1); PG8_BAR; PG8_SCHED;
;             PG8_LDA(At, 1, 1); PG8_STAGE(PG8_SB(1, 0), b3, voffB); PG8_STAGE(PG8_SB(1, 1), b3 + hB1, voffB1); PG8_STAGE(PG8_SA(1, 0), a3, voffA);
;             PG8_WAIT_V(8);
;             if constexpr (epi_pre<Epi>::value) { if (last) E.pre(pre, cur, wr, wc, lane); }
;             PG8_WAIT_L(0); PG8_BAR; PG8_MMA(1, 0, At, B0); PG8_MMA(1, 1, At, B1); PG8_BAR; PG8_SCHED;
.LBB0_2633:
	s_add_u32 s42, s30, s36
	s_addc_u32 s43, s31, s37
	s_add_u32 s40, s42, 0x100
	s_addc_u32 s41, s43, 0
	s_and_b64 s[38:39], s[2:3], exec
	s_cselect_b32 s39, s1, s41
	s_cselect_b32 s38, s23, s40
	s_add_u32 s36, s28, s36
	s_addc_u32 s37, s29, s37
	s_add_u32 s36, s36, 0x100
	s_addc_u32 s37, s37, 0
	s_and_b64 s[2:3], s[2:3], exec
	s_cselect_b32 s41, s21, s37
	s_cselect_b32 s40, s67, s36
	s_add_u32 s74, s42, 0x40080
	s_addc_u32 s75, s43, 0
	s_add_i32 s77, s61, s49
	s_add_i32 m0, s50, 0xc000
	s_add_i32 s76, s50, 0xe000
	s_add_i32 s78, s77, 0x2000
	v_add_u32_e32 v2, s61, v184
	s_add_u32 s42, s40, 0x1000
	ds_read_b128 v[158:161], v2
	ds_read_b128 v[162:165], v2 offset:1024
	ds_read_b128 v[186:189], v2 offset:2048
	ds_read_b128 v[190:193], v2 offset:3072
	v_add_u32_e32 v2, s62, v184
	s_addc_u32 s43, s41, 0
	s_add_i32 s79, s62, s49
	ds_read_b128 v[138:141], v2
	ds_read_b128 v[142:145], v2 offset:1024
	ds_read_b128 v[146:149], v2 offset:2048
	ds_read_b128 v[134:137], v2 offset:3072
	s_add_i32 s80, s79, 0x2000
	s_add_i32 s73, 0, 0x18000
	s_add_i32 s72, 0, 0x1c000
	s_add_u32 s2, s38, 0x40000
	s_addc_u32 s3, s39, 0
	s_add_i32 s69, s73, s49
	s_add_i32 s68, s69, 0x2000
	s_add_u32 s36, s40, 0x1080
	s_addc_u32 s37, s41, 0
	s_add_i32 s71, s72, s49
	s_add_i32 s70, s71, 0x2000
	v_lshl_add_u64 v[4:5], s[74:75], 0, v[166:167]
	ds_read_b128 v[150:153], v185
	ds_read_b128 v[154:157], v185 offset:1024
	ds_read_b128 v[194:197], v185 offset:2048
	ds_read_b128 v[198:201], v185 offset:3072
	ds_read_b128 v[202:205], v185 offset:4096
	ds_read_b128 v[206:209], v185 offset:5120
	ds_read_b128 v[210:213], v185 offset:6144
	ds_read_b128 v[214:217], v185 offset:7168
	global_load_lds_dwordx4 v[4:5], off
	v_lshl_add_u64 v[4:5], s[74:75], 0, v[170:171]
	s_mov_b32 m0, s76
	s_nop 0
	global_load_lds_dwordx4 v[4:5], off
	s_waitcnt vmcnt(8)
	s_waitcnt lgkmcnt(0)
	s_barrier
	s_setprio 1
	s_waitcnt lgkmcnt(0)
	v_mfma_f32_16x16x32_bf16 v[218:221], v[158:161], v[150:153], v[78:81]
	v_mfma_f32_16x16x32_bf16 v[78:81], v[162:165], v[154:157], v[218:221]
	v_mfma_f32_16x16x32_bf16 v[222:225], v[186:189], v[150:153], v[62:65]
	v_mfma_f32_16x16x32_bf16 v[226:229], v[158:161], v[194:197], v[130:133]
	v_mfma_f32_16x16x32_bf16 v[230:233], v[186:189], v[194:197], v[126:129]
	v_mfma_f32_16x16x32_bf16 v[234:237], v[158:161], v[202:205], v[74:77]
	v_mfma_f32_16x16x32_bf16 v[238:241], v[186:189], v[202:205], v[102:105]
	v_mfma_f32_16x16x32_bf16 v[218:221], v[158:161], v[210:213], v[122:125]
	v_mfma_f32_16x16x32_bf16 v[114:117], v[186:189], v[210:213], v[114:117]
	v_mfma_f32_16x16x32_bf16 v[62:65], v[190:193], v[154:157], v[222:225]
	v_mfma_f32_16x16x32_bf16 v[130:133], v[162:165], v[198:201], v[226:229]
	v_mfma_f32_16x16x32_bf16 v[126:129], v[190:193], v[198:201], v[230:233]
	v_mfma_f32_16x16x32_bf16 v[74:77], v[162:165], v[206:209], v[234:237]
	v_mfma_f32_16x16x32_bf16 v[102:105], v[190:193], v[206:209], v[238:241]
	v_mfma_f32_16x16x32_bf16 v[122:125], v[162:165], v[214:217], v[218:221]
	v_mfma_f32_16x16x32_bf16 v[114:117], v[190:193], v[214:217], v[114:117]
	s_setprio 0
	s_setprio 1
	v_mfma_f32_16x16x32_bf16 v[218:221], v[138:141], v[150:153], v[50:53]
	v_mfma_f32_16x16x32_bf16 v[50:53], v[142:145], v[154:157], v[218:221]
	v_mfma_f32_16x16x32_bf16 v[222:225], v[146:149], v[150:153], v[30:33]
	v_mfma_f32_16x16x32_bf16 v[226:229], v[138:141], v[194:197], v[110:113]
	v_mfma_f32_16x16x32_bf16 v[230:233], v[146:149], v[194:197], v[34:37]
	v_mfma_f32_16x16x32_bf16 v[234:237], v[138:141], v[202:205], v[46:49]
	v_mfma_f32_16x16x32_bf16 v[238:241], v[146:149], v[202:205], v[18:21]
	v_mfma_f32_16x16x32_bf16 v[150:153], v[138:141], v[210:213], v[90:93]
	v_mfma_f32_16x16x32_bf16 v[26:29], v[146:149], v[210:213], v[26:29]
	v_mfma_f32_16x16x32_bf16 v[30:33], v[134:137], v[154:157], v[222:225]
	v_mfma_f32_16x16x32_bf16 v[110:113], v[142:145], v[198:201], v[226:229]
	v_mfma_f32_16x16x32_bf16 v[34:37], v[134:137], v[198:201], v[230:233]
	v_mfma_f32_16x16x32_bf16 v[46:49], v[142:145], v[206:209], v[234:237]
	v_mfma_f32_16x16x32_bf16 v[18:21], v[134:137], v[206:209], v[238:241]
	v_mfma_f32_16x16x32_bf16 v[90:93], v[142:145], v[214:217], v[150:153]
	v_mfma_f32_16x16x32_bf16 v[26:29], v[134:137], v[214:217], v[26:29]
	s_setprio 0
	s_barrier
	s_mov_b32 m0, s77
	v_lshl_add_u64 v[150:151], s[40:41], 0, v[168:169]
	ds_read_b128 v[194:197], v185 offset:16384
	ds_read_b128 v[198:201], v185 offset:17408
	ds_read_b128 v[202:205], v185 offset:18432
	ds_read_b128 v[206:209], v185 offset:19456
	ds_read_b128 v[210:213], v185 offset:20480
	ds_read_b128 v[214:217], v185 offset:21504
	ds_read_b128 v[218:221], v185 offset:22528
	ds_read_b128 v[222:225], v185 offset:23552
	global_load_lds_dwordx4 v[150:151], off
	v_lshl_add_u64 v[152:153], s[40:41], 0, v[172:173]
	s_mov_b32 m0, s78
	v_lshl_add_u64 v[4:5], s[42:43], 0, v[168:169]
	global_load_lds_dwordx4 v[152:153], off
	s_mov_b32 m0, s79
	v_lshl_add_u64 v[154:155], s[38:39], 0, v[166:167]
	global_load_lds_dwordx4 v[4:5], off
	v_lshl_add_u64 v[4:5], s[42:43], 0, v[172:173]
	s_mov_b32 m0, s80
	v_lshl_add_u64 v[156:157], s[38:39], 0, v[170:171]
	global_load_lds_dwordx4 v[4:5], off
	s_mov_b32 m0, s50
	s_nop 0
	global_load_lds_dwordx4 v[154:155], off
	s_mov_b32 m0, s51
	s_nop 0
	global_load_lds_dwordx4 v[156:157], off
	s_waitcnt vmcnt(8)
	s_waitcnt lgkmcnt(0)
	s_barrier
; #define PG8_STAGE(bufoff, gbase, voff) do { _Pragma("unroll") for (int _i = 0; _i < 2; ++_i) \
;         __builtin_amdgcn_global_load_lds((const unsigned*)((const char*)(gbase) + (voff)[_i]), (PG8_LAS unsigned*)(lds + (bufoff) + ldsw + _i * 8192), 16, 0, 0); } while (0)
; #define PG8_LDA(dst, b, h) do { _Pragma("unroll") for (int m = 0; m < 4; ++m) _Pragma("unroll") for (int k = 0; k < 2; ++k) dst[m][k] = *(const PG8_LAS bf16x8*)(lds + PG8_SA(b, h) + aoff + m * 2048 + k * 1024); } while (0)
; #define PG8_LDB(dst, b, h) do { _Pragma("unroll") for (int n = 0; n < 2; ++n) _Pragma("unroll") for (int k = 0; k < 2; ++k) dst[n][k] = *(const PG8_LAS bf16x8*)(lds + PG8_SB(b, h) + boff + n * 2048 + k * 1024); } while (0)
; #define PG8_WAIT_V(n) asm volatile("s_waitcnt vmcnt(" #n ")" ::: "memory")
; #define PG8_WAIT_L(n) asm volatile("s_waitcnt lgkmcnt(" #n ")" ::: "memory")
; #define PG8_BAR __builtin_amdgcn_s_barrier()
; #define PG8_SCHED __builtin_amdgcn_sched_barrier(0)
; template <class Epi, class Sched, class Gemm, bool ALIGN_EPI = false, bool SP2 = false>
; __device__ __forceinline__ void gemm_phase(PG8_LAS unsigned char* lds, const Gemm g, const Sched& S, const Epi& E) {
;     ...
;             PG8_LDB(B0, 0, 0); PG8_LDB(B1, 0, 1); PG8_SCHED; PG8_LDA(At, 0, 0); PG8_STAGE(PG8_SA(1, 1), a1 + hstepA, voffA);
;             PG8_WAIT_V(8); PG8_WAIT_L(0); PG8_BAR; PG8_MMA(0, 0, At, B0); PG8_MMA(0, 1, At, B1); PG8_BAR; PG8_SCHED;
;             PG8_LDA(At, 0, 1); PG8_STAGE(PG8_SB(0, 0), b2, voffB); PG8_STAGE(PG8_SB(0, 1), b2 + hB1, voffB1); PG8_STAGE(PG8_SA(0, 0), a2, voffA);
;             PG8_WAIT_V(8); PG8_WAIT_L(0); PG8_BAR; PG8_MMA(1, 0, At, B0); PG8_MMA(1, 1, At, B1); PG8_BAR; PG8_SCHED;
;             PG8_LDB(B0, 1, 0); PG8_LDB(B1, 1, 1); PG8_SCHED; PG8_LDA(At, 1, 0); PG8_STAGE(PG8_SA(0, 1), a2 + hstepA, voffA);
;             PG8_WAIT_V(8); PG8_WAIT_L(0); PG8_BAR; PG8_MMA(0, 0, At, B0); PG8_MMA(0, 1, At, B1); PG8_BAR; PG8_SCHED;
;             PG8_LDA(At, 1, 1); PG8_STAGE(PG8_SB(1, 0), b3, voffB); PG8_STAGE(PG8_SB(1, 1), b3 + hB1, voffB1); PG8_STAGE(PG8_SA(1, 0), a3, voffA);
;             PG8_WAIT_V(8);
;             if constexpr (epi_pre<Epi>::value) { if (last) E.pre(pre, cur, wr, wc, lane); }
;             PG8_WAIT_L(0); PG8_BAR; PG8_MMA(1, 0, At, B0); PG8_MMA(1, 1, At, B1); PG8_BAR; PG8_SCHED;
	s_setprio 1
	s_waitcnt lgkmcnt(0)
	v_mfma_f32_16x16x32_bf16 v[226:229], v[158:161], v[194:197], v[70:73]
	v_mfma_f32_16x16x32_bf16 v[70:73], v[162:165], v[198:201], v[226:229]
	v_mfma_f32_16x16x32_bf16 v[230:233], v[186:189], v[194:197], v[58:61]
	v_mfma_f32_16x16x32_bf16 v[234:237], v[158:161], v[202:205], v[98:101]
	v_mfma_f32_16x16x32_bf16 v[238:241], v[186:189], v[202:205], v[86:89]
	v_mfma_f32_16x16x32_bf16 v[242:245], v[158:161], v[210:213], v[66:69]
	v_mfma_f32_16x16x32_bf16 v[246:249], v[186:189], v[210:213], v[94:97]
	v_mfma_f32_16x16x32_bf16 v[226:229], v[158:161], v[218:221], v[118:121]
	v_mfma_f32_16x16x32_bf16 v[106:109], v[186:189], v[218:221], v[106:109]
	v_mfma_f32_16x16x32_bf16 v[58:61], v[190:193], v[198:201], v[230:233]
	v_mfma_f32_16x16x32_bf16 v[98:101], v[162:165], v[206:209], v[234:237]
	v_mfma_f32_16x16x32_bf16 v[86:89], v[190:193], v[206:209], v[238:241]
	v_mfma_f32_16x16x32_bf16 v[66:69], v[162:165], v[214:217], v[242:245]
	v_mfma_f32_16x16x32_bf16 v[94:97], v[190:193], v[214:217], v[246:249]
	v_mfma_f32_16x16x32_bf16 v[118:121], v[162:165], v[222:225], v[226:229]
	v_mfma_f32_16x16x32_bf16 v[106:109], v[190:193], v[222:225], v[106:109]
	s_setprio 0
	s_setprio 1
	v_mfma_f32_16x16x32_bf16 v[158:161], v[138:141], v[194:197], v[42:45]
	v_mfma_f32_16x16x32_bf16 v[42:45], v[142:145], v[198:201], v[158:161]
	v_mfma_f32_16x16x32_bf16 v[162:165], v[146:149], v[194:197], v[6:9]
	v_mfma_f32_16x16x32_bf16 v[186:189], v[138:141], v[202:205], v[54:57]
	v_mfma_f32_16x16x32_bf16 v[190:193], v[146:149], v[202:205], v[10:13]
	v_mfma_f32_16x16x32_bf16 v[226:229], v[138:141], v[210:213], v[38:41]
	v_mfma_f32_16x16x32_bf16 v[230:233], v[146:149], v[210:213], v[14:17]
	v_mfma_f32_16x16x32_bf16 v[158:161], v[138:141], v[218:221], v[82:85]
	v_mfma_f32_16x16x32_bf16 v[22:25], v[146:149], v[218:221], v[22:25]
	v_mfma_f32_16x16x32_bf16 v[4:7], v[134:137], v[198:201], v[162:165]
	v_mfma_f32_16x16x32_bf16 v[54:57], v[142:145], v[206:209], v[186:189]
	v_mfma_f32_16x16x32_bf16 v[10:13], v[134:137], v[206:209], v[190:193]
	v_mfma_f32_16x16x32_bf16 v[38:41], v[142:145], v[214:217], v[226:229]
	v_mfma_f32_16x16x32_bf16 v[14:17], v[134:137], v[214:217], v[230:233]
	v_mfma_f32_16x16x32_bf16 v[82:85], v[142:145], v[222:225], v[158:161]
	v_mfma_f32_16x16x32_bf16 v[22:25], v[134:137], v[222:225], v[22:25]
	s_setprio 0
	s_barrier
	v_add_u32_e32 v2, s73, v184
	ds_read_b128 v[158:161], v2
	ds_read_b128 v[162:165], v2 offset:1024
	ds_read_b128 v[186:189], v2 offset:2048
	ds_read_b128 v[190:193], v2 offset:3072
	v_add_u32_e32 v2, s72, v184
	ds_read_b128 v[138:141], v2
	ds_read_b128 v[142:145], v2 offset:1024
	ds_read_b128 v[146:149], v2 offset:2048
	ds_read_b128 v[134:137], v2 offset:3072
	s_mov_b32 m0, s52
	v_lshl_add_u64 v[8:9], s[2:3], 0, v[166:167]
	ds_read_b128 v[194:197], v185 offset:32768
	ds_read_b128 v[198:201], v185 offset:33792
	ds_read_b128 v[202:205], v185 offset:34816
	ds_read_b128 v[206:209], v185 offset:35840
	ds_read_b128 v[210:213], v185 offset:36864
	ds_read_b128 v[214:217], v185 offset:37888
	ds_read_b128 v[218:221], v185 offset:38912
	ds_read_b128 v[222:225], v185 offset:39936
	global_load_lds_dwordx4 v[8:9], off
	v_lshl_add_u64 v[8:9], s[2:3], 0, v[170:171]
	s_mov_b32 m0, s53
	s_nop 0
	global_load_lds_dwordx4 v[8:9], off
	s_waitcnt vmcnt(8)
	s_waitcnt lgkmcnt(0)
	s_barrier
	s_setprio 1
	s_waitcnt lgkmcnt(0)
	v_mfma_f32_16x16x32_bf16 v[226:229], v[158:161], v[194:197], v[78:81]
	v_mfma_f32_16x16x32_bf16 v[78:81], v[162:165], v[198:201], v[226:229]
	v_mfma_f32_16x16x32_bf16 v[230:233], v[186:189], v[194:197], v[62:65]
	v_mfma_f32_16x16x32_bf16 v[234:237], v[158:161], v[202:205], v[130:133]
	v_mfma_f32_16x16x32_bf16 v[238:241], v[186:189], v[202:205], v[126:129]
	v_mfma_f32_16x16x32_bf16 v[242:245], v[158:161], v[210:213], v[74:77]
	v_mfma_f32_16x16x32_bf16 v[246:249], v[186:189], v[210:213], v[102:105]
	v_mfma_f32_16x16x32_bf16 v[226:229], v[158:161], v[218:221], v[122:125]
	v_mfma_f32_16x16x32_bf16 v[114:117], v[186:189], v[218:221], v[114:117]
	v_mfma_f32_16x16x32_bf16 v[62:65], v[190:193], v[198:201], v[230:233]
	v_mfma_f32_16x16x32_bf16 v[130:133], v[162:165], v[206:209], v[234:237]
	v_mfma_f32_16x16x32_bf16 v[126:129], v[190:193], v[206:209], v[238:241]
	v_mfma_f32_16x16x32_bf16 v[74:77], v[162:165], v[214:217], v[242:245]
	v_mfma_f32_16x16x32_bf16 v[102:105], v[190:193], v[214:217], v[246:249]
	v_mfma_f32_16x16x32_bf16 v[122:125], v[162:165], v[222:225], v[226:229]
	v_mfma_f32_16x16x32_bf16 v[114:117], v[190:193], v[222:225], v[114:117]
	s_setprio 0
	s_setprio 1
	v_mfma_f32_16x16x32_bf16 v[226:229], v[138:141], v[194:197], v[50:53]
	v_mfma_f32_16x16x32_bf16 v[50:53], v[142:145], v[198:201], v[226:229]
	v_mfma_f32_16x16x32_bf16 v[230:233], v[146:149], v[194:197], v[30:33]
	v_mfma_f32_16x16x32_bf16 v[234:237], v[138:141], v[202:205], v[110:113]
	v_mfma_f32_16x16x32_bf16 v[238:241], v[146:149], v[202:205], v[34:37]
	v_mfma_f32_16x16x32_bf16 v[242:245], v[138:141], v[210:213], v[46:49]
	v_mfma_f32_16x16x32_bf16 v[246:249], v[146:149], v[210:213], v[18:21]
	v_mfma_f32_16x16x32_bf16 v[194:197], v[138:141], v[218:221], v[90:93]
	v_mfma_f32_16x16x32_bf16 v[26:29], v[146:149], v[218:221], v[26:29]
	v_mfma_f32_16x16x32_bf16 v[30:33], v[134:137], v[198:201], v[230:233]
	v_mfma_f32_16x16x32_bf16 v[110:113], v[142:145], v[206:209], v[234:237]
	v_mfma_f32_16x16x32_bf16 v[34:37], v[134:137], v[206:209], v[238:241]
	v_mfma_f32_16x16x32_bf16 v[46:49], v[142:145], v[214:217], v[242:245]
	v_mfma_f32_16x16x32_bf16 v[18:21], v[134:137], v[214:217], v[246:249]
	v_mfma_f32_16x16x32_bf16 v[90:93], v[142:145], v[222:225], v[194:197]
	v_mfma_f32_16x16x32_bf16 v[26:29], v[134:137], v[222:225], v[26:29]
	s_setprio 0
	s_barrier
; #define PG8_WAIT_V(n) asm volatile("s_waitcnt vmcnt(" #n ")" ::: "memory")
;     __device__ __forceinline__ void chain(f32x4 (&acc)[2][2][4][2], const Unit& u, int wr, int wc, int fr, int fq) const {
;     ...
;         const bool last = (u.sub == 3);
; template <class Epi, class Sched, class Gemm, bool ALIGN_EPI = false, bool SP2 = false>
; __device__ __forceinline__ void gemm_phase(PG8_LAS unsigned char* lds, const Gemm g, const Sched& S, const Epi& E) {
;     ...
;             PG8_WAIT_V(8); PG8_WAIT_L(0); PG8_BAR; PG8_MMA(0, 0, At, B0); PG8_MMA(0, 1, At, B1); PG8_BAR; PG8_SCHED;
;             PG8_LDA(At, 1, 1); PG8_STAGE(PG8_SB(1, 0), b3, voffB); PG8_STAGE(PG8_SB(1, 1), b3 + hB1, voffB1); PG8_STAGE(PG8_SA(1, 0), a3, voffA);
;             PG8_WAIT_V(8);
;             if constexpr (epi_pre<Epi>::value) { if (last) E.pre(pre, cur, wr, wc, lane); }
;             PG8_WAIT_L(0); PG8_BAR; PG8_MMA(1, 0, At, B0); PG8_MMA(1, 1, At, B1); PG8_BAR; PG8_SCHED;
;             } else {
;             PG8_LDB(B0, 0, 0); PG8_SCHED; PG8_LDA(At, 0, 0); PG8_STAGE(PG8_SA(1, 1), a1 + hstepA, voffA);
;             PG8_WAIT_L(8); PG8_BAR; PG8_WAIT_L(0); PG8_MMA(0, 0, At, B0); PG8_BAR; PG8_SCHED;
;             PG8_LDB(B1, 0, 1); PG8_STAGE(PG8_SB(0, 0), b2, voffB);
;             PG8_BAR; PG8_WAIT_L(0); PG8_MMA(0, 1, At, B1); PG8_BAR;
;             PG8_LDA(At, 0, 1); PG8_STAGE(PG8_SA(0, 0), a2, voffA);
;             PG8_BAR; PG8_WAIT_L(0); PG8_MMA(1, 0, At, B0); PG8_BAR; PG8_SCHED;
;             PG8_STAGE(PG8_SB(0, 1), b2 + hB1, voffB1);
;             PG8_WAIT_V(6); PG8_BAR; PG8_MMA(1, 1, At, B1); PG8_BAR;
;             PG8_LDB(B0, 1, 0); PG8_SCHED; PG8_LDA(At, 1, 0); PG8_STAGE(PG8_SA(0, 1), a2 + hstepA, voffA);
;             PG8_WAIT_L(8); PG8_BAR; PG8_WAIT_L(0); PG8_MMA(0, 0, At, B0); PG8_BAR; PG8_SCHED;
;             PG8_LDB(B1, 1, 1); PG8_STAGE(PG8_SB(1, 0), b3, voffB);
;             PG8_BAR; PG8_WAIT_L(0); PG8_MMA(0, 1, At, B1); PG8_BAR;
;             PG8_LDA(At, 1, 1); PG8_STAGE(PG8_SA(1, 0), a3, voffA);
;             PG8_BAR; PG8_WAIT_L(0); PG8_MMA(1, 0, At, B0); PG8_BAR; PG8_SCHED;
;             PG8_STAGE(PG8_SB(1, 1), b3 + hB1, voffB1);
;             PG8_WAIT_V(6); PG8_BAR; PG8_MMA(1, 1, At, B1); PG8_BAR;
;             }
;         }
;         if constexpr (ALIGN_EPI) { if (wr == 0) PG8_BAR; }
;         if constexpr (epi_chain<Epi>::value) { E.chain(acc, cur, wr, wc, fr, fq); S.done(cur); }
	s_mov_b32 m0, s69
	v_lshl_add_u64 v[8:9], v[150:151], 0, s[16:17]
	ds_read_b128 v[194:197], v185 offset:49152
	ds_read_b128 v[198:201], v185 offset:50176
	ds_read_b128 v[202:205], v185 offset:51200
	ds_read_b128 v[206:209], v185 offset:52224
	ds_read_b128 v[210:213], v185 offset:53248
	ds_read_b128 v[214:217], v185 offset:54272
	ds_read_b128 v[218:221], v185 offset:55296
	ds_read_b128 v[222:225], v185 offset:56320
	global_load_lds_dwordx4 v[8:9], off
	v_lshl_add_u64 v[8:9], v[152:153], 0, s[16:17]
	s_mov_b32 m0, s68
	s_nop 0
	global_load_lds_dwordx4 v[8:9], off
	v_lshl_add_u64 v[8:9], s[36:37], 0, v[168:169]
	s_mov_b32 m0, s71
	s_nop 0
	global_load_lds_dwordx4 v[8:9], off
	v_lshl_add_u64 v[8:9], s[36:37], 0, v[172:173]
	s_mov_b32 m0, s70
	s_nop 0
	global_load_lds_dwordx4 v[8:9], off
	v_lshl_add_u64 v[8:9], v[154:155], 0, s[16:17]
	s_mov_b32 m0, s57
	s_nop 0
	global_load_lds_dwordx4 v[8:9], off
	v_lshl_add_u64 v[8:9], v[156:157], 0, s[16:17]
	s_mov_b32 m0, s58
	s_nop 0
	global_load_lds_dwordx4 v[8:9], off
	s_waitcnt vmcnt(8)
	s_waitcnt lgkmcnt(0)
	s_barrier
	s_setprio 1
	s_waitcnt lgkmcnt(0)
	v_mfma_f32_16x16x32_bf16 v[150:153], v[158:161], v[194:197], v[70:73]
	v_mfma_f32_16x16x32_bf16 v[70:73], v[162:165], v[198:201], v[150:153]
	v_mfma_f32_16x16x32_bf16 v[154:157], v[186:189], v[194:197], v[58:61]
	v_mfma_f32_16x16x32_bf16 v[226:229], v[158:161], v[202:205], v[98:101]
	v_mfma_f32_16x16x32_bf16 v[230:233], v[186:189], v[202:205], v[86:89]
	v_mfma_f32_16x16x32_bf16 v[234:237], v[158:161], v[210:213], v[66:69]
	v_mfma_f32_16x16x32_bf16 v[238:241], v[186:189], v[210:213], v[94:97]
	v_mfma_f32_16x16x32_bf16 v[150:153], v[158:161], v[218:221], v[118:121]
	v_mfma_f32_16x16x32_bf16 v[106:109], v[186:189], v[218:221], v[106:109]
	v_mfma_f32_16x16x32_bf16 v[58:61], v[190:193], v[198:201], v[154:157]
	v_mfma_f32_16x16x32_bf16 v[98:101], v[162:165], v[206:209], v[226:229]
	v_mfma_f32_16x16x32_bf16 v[86:89], v[190:193], v[206:209], v[230:233]
	v_mfma_f32_16x16x32_bf16 v[66:69], v[162:165], v[214:217], v[234:237]
	v_mfma_f32_16x16x32_bf16 v[94:97], v[190:193], v[214:217], v[238:241]
	v_mfma_f32_16x16x32_bf16 v[118:121], v[162:165], v[222:225], v[150:153]
	v_mfma_f32_16x16x32_bf16 v[106:109], v[190:193], v[222:225], v[106:109]
	s_setprio 0
	s_setprio 1
	v_mfma_f32_16x16x32_bf16 v[150:153], v[138:141], v[194:197], v[42:45]
	v_mfma_f32_16x16x32_bf16 v[42:45], v[142:145], v[198:201], v[150:153]
	v_mfma_f32_16x16x32_bf16 v[154:157], v[146:149], v[194:197], v[4:7]
	v_mfma_f32_16x16x32_bf16 v[158:161], v[138:141], v[202:205], v[54:57]
	v_mfma_f32_16x16x32_bf16 v[162:165], v[146:149], v[202:205], v[10:13]
	v_mfma_f32_16x16x32_bf16 v[186:189], v[138:141], v[210:213], v[38:41]
	v_mfma_f32_16x16x32_bf16 v[190:193], v[146:149], v[210:213], v[14:17]
	v_mfma_f32_16x16x32_bf16 v[150:153], v[138:141], v[218:221], v[82:85]
	v_mfma_f32_16x16x32_bf16 v[22:25], v[146:149], v[218:221], v[22:25]
	v_mfma_f32_16x16x32_bf16 v[6:9], v[134:137], v[198:201], v[154:157]
	v_mfma_f32_16x16x32_bf16 v[54:57], v[142:145], v[206:209], v[158:161]
	v_mfma_f32_16x16x32_bf16 v[10:13], v[134:137], v[206:209], v[162:165]
	v_mfma_f32_16x16x32_bf16 v[38:41], v[142:145], v[214:217], v[186:189]
	v_mfma_f32_16x16x32_bf16 v[14:17], v[134:137], v[214:217], v[190:193]
	v_mfma_f32_16x16x32_bf16 v[82:85], v[142:145], v[222:225], v[150:153]
	v_mfma_f32_16x16x32_bf16 v[22:25], v[134:137], v[222:225], v[22:25]
	s_setprio 0
	s_barrier
	s_andn2_b64 vcc, exec, s[34:35]
	s_mov_b64 s[2:3], -1
	s_mov_b64 s[34:35], 0
	s_mov_b64 s[36:37], 0x100
	s_cbranch_vccz .LBB0_2633
	s_lshl_b32 s0, s0, 8
	s_lshl_b32 s1, s6, 8
	s_or_b32 s21, s0, s59
	s_lshl_b32 s0, s7, 10
	s_add_i32 s6, s1, s56
	s_add_i32 s23, s0, 0xc00
	s_cmp_eq_u32 s7, 3
	v_mov_b32_e32 v2, v181
	v_mov_b32_e32 v4, v1
	s_cselect_b64 s[0:1], -1, 0
	s_and_b64 s[2:3], s[0:1], exec
	s_cselect_b32 s2, 0, s23
	v_add_u32_e32 v4, s6, v4
	v_mul_lo_u32 v5, v4, s63
	v_lshlrev_b32_e32 v2, 4, v2
	s_cselect_b32 s28, s54, s14
	s_cselect_b32 s29, s55, s15
	s_add_i32 s3, s2, 0x400
	v_add3_u32 v180, s21, v2, v5
	s_cmp_lt_u32 s7, 2
	v_add_u32_e32 v2, s2, v180
	s_cselect_b32 s3, s3, 0
	global_load_dwordx4 v[142:145], v2, s[14:15]
	v_add_u32_e32 v2, s3, v180
	v_cndmask_b32_e64 v2, v2, 0, s[0:1]
	global_load_dwordx4 v[146:149], v2, s[28:29]
	v_add_u32_e32 v2, 0x22000, v180
	v_add_u32_e32 v138, 0x66000, v180
	v_add_u32_e32 v5, 0x44000, v180
	v_add_u32_e32 v134, s2, v2
	v_add_u32_e32 v136, s2, v138
	v_add_u32_e32 v2, s3, v2
	v_add_u32_e32 v138, s3, v138
	v_add_u32_e32 v135, s2, v5
	v_add_u32_e32 v5, s3, v5
	v_cndmask_b32_e64 v2, v2, 0, s[0:1]
	v_cndmask_b32_e64 v138, v138, 0, s[0:1]
	global_load_dwordx4 v[150:153], v134, s[14:15]
	global_load_dwordx4 v[154:157], v135, s[14:15]
	s_nop 0
	global_load_dwordx4 v[134:137], v136, s[14:15]
	v_cndmask_b32_e64 v5, v5, 0, s[0:1]
	global_load_dwordx4 v[158:161], v2, s[28:29]
	global_load_dwordx4 v[162:165], v5, s[28:29]
	s_nop 0
	global_load_dwordx4 v[138:141], v138, s[28:29]
	v_mad_u64_u32 v[4:5], s[30:31], v4, s64, v[180:181]
	s_and_b64 vcc, exec, s[18:19]
	s_cbranch_vccz .LBB0_2636
	s_barrier
